# P5/P12 row-block visiting order remapped to follow the up GEMM per-XCD write order (MALL residency assumption)
# speedup vs baseline: 1.0015x; 1.0015x over previous
.LBB0_203:
	s_mul_hi_i32 s2, s26, 0xd1745d17
	s_lshr_b32 s3, s2, 31
	s_ashr_i32 s20, s2, 2
	s_mul_hi_i32 s2, s26, 0x2e8ba2e9
	s_add_i32 s20, s20, s3
	s_lshr_b32 s3, s2, 31
	s_ashr_i32 s2, s2, 2
	s_add_i32 s2, s2, s3
	s_mul_i32 s2, s2, 22
	s_sub_i32 s19, s26, s2
	s_sub_i32 s2, 0, s20
	s_and_b32 s3, s2, 7
	s_lshr_b32 s2, s2, 3
	s_mul_i32 s3, s3, 33
	s_sub_i32 s3, s3, s2
	s_addk_i32 s3, 0xff19
	s_mov_b32 s20, s3
	v_lshl_or_b32 v64, s19, 7, v92
	v_ashrrev_i32_e32 v65, 31, v64
	v_add_u32_e32 v98, 0xb00, v64
	v_lshlrev_b64 v[66:67], 2, v[64:65]
	v_lshl_add_u64 v[0:1], s[6:7], 0, v[66:67]
	v_lshlrev_b64 v[68:69], 2, v[98:99]
	s_add_i32 s22, s20, 0x107
	v_lshl_add_u64 v[2:3], s[6:7], 0, v[68:69]
	v_lshl_add_u64 v[4:5], s[10:11], 0, v[66:67]
	v_lshl_add_u64 v[6:7], s[10:11], 0, v[68:69]
	global_load_dwordx2 v[70:71], v[0:1], off
	global_load_dwordx2 v[72:73], v[2:3], off
	global_load_dwordx2 v[74:75], v[4:5], off
	global_load_dwordx2 v[76:77], v[6:7], off
	v_lshl_add_u64 v[0:1], s[12:13], 0, v[66:67]
	s_lshl_b32 s21, s22, 7
	v_lshl_add_u64 v[2:3], s[12:13], 0, v[68:69]
	global_load_dwordx2 v[78:79], v[0:1], off
	global_load_dwordx2 v[80:81], v[2:3], off
	v_or_b32_e32 v0, s21, v194
	v_mov_b32_e32 v1, v99
	v_lshlrev_b64 v[0:1], 7, v[0:1]
	v_lshl_add_u64 v[4:5], s[8:9], 0, v[0:1]
	s_waitcnt vmcnt(0)
	v_add_co_u32_e32 v24, vcc, s33, v4
	v_lshl_add_u64 v[0:1], v[4:5], 0, s[74:75]
	s_nop 0
	v_addc_co_u32_e32 v25, vcc, 0, v5, vcc
	global_load_dwordx4 v[20:23], v[4:5], off offset:48
	global_load_dwordx4 v[36:39], v[4:5], off offset:32
	global_load_dwordx4 v[48:51], v[4:5], off offset:16
	global_load_dwordx4 v[56:59], v[4:5], off
	global_load_dwordx4 v[60:63], v[24:25], off
	global_load_dwordx4 v[28:31], v[0:1], off offset:48
	global_load_dwordx4 v[44:47], v[0:1], off offset:32
	global_load_dwordx4 v[52:55], v[0:1], off offset:16
	s_nop 0
	global_load_dwordx4 v[0:3], v[4:5], off offset:112
	global_load_dwordx4 v[8:11], v[4:5], off offset:96
	global_load_dwordx4 v[16:19], v[4:5], off offset:80
	global_load_dwordx4 v[32:35], v[4:5], off offset:64
	s_mov_b64 s[2:3], 0x2040
	v_lshl_add_u64 v[26:27], v[4:5], 0, s[2:3]
	global_load_dwordx4 v[4:7], v[26:27], off offset:48
	global_load_dwordx4 v[12:15], v[26:27], off offset:32
	global_load_dwordx4 v[40:43], v[24:25], off offset:64
	s_nop 0
	global_load_dwordx4 v[24:27], v[26:27], off offset:16
	s_and_b32 s18, s22, 63
	s_cmp_lg_u32 s18, 0
	s_cselect_b64 s[2:3], -1, 0
	s_cmpk_lt_i32 s22, 0x100
	s_cselect_b64 s[14:15], -1, 0
	s_cmpk_gt_i32 s22, 0xff
	s_cselect_b64 s[16:17], -1, 0
	s_and_b64 s[24:25], s[14:15], s[2:3]
	v_cndmask_b32_e64 v82, 0, 1, s[24:25]
	v_cmp_ne_u32_e64 s[2:3], 1, v82
	s_andn2_b64 vcc, exec, s[24:25]
	v_mov_b32_e32 v82, 0
	s_cbranch_vccnz .LBB0_205
	v_add_u32_e32 v82, s21, v93
	v_ashrrev_i32_e32 v83, 31, v82
	v_lshlrev_b64 v[82:83], 7, v[82:83]
	v_lshl_add_u64 v[90:91], s[8:9], 0, v[82:83]
	global_load_dwordx4 v[82:85], v[90:91], off offset:48
	global_load_dwordx4 v[86:89], v[90:91], off offset:32
	global_load_dwordx4 v[100:103], v[90:91], off
	global_load_dwordx4 v[104:107], v[90:91], off offset:16
	s_waitcnt vmcnt(3)
	v_add_f32_e32 v112, v82, v83
	v_add_f32_e32 v114, v84, v85
	s_waitcnt vmcnt(1)
	v_mov_b32_e32 v108, v100
	s_waitcnt vmcnt(0)
	v_mov_b32_e32 v109, v104
	v_mov_b32_e32 v104, v101
	v_pk_add_f32 v[100:101], v[108:109], v[104:105]
	v_mov_b32_e32 v104, v102
	v_mov_b32_e32 v105, v106
	v_mov_b32_e32 v106, v103
	v_pk_add_f32 v[102:103], v[104:105], v[106:107]
	s_nop 0
	v_pk_add_f32 v[100:101], v[100:101], v[102:103]
	s_nop 0
	v_add_f32_e32 v97, 0, v100
	v_add_f32_e32 v108, v97, v101
	v_mov_b32_e32 v100, v87
	v_mov_b32_e32 v101, v88
	v_mov_b32_e32 v87, v89
	v_pk_add_f32 v[86:87], v[100:101], v[86:87]
	s_nop 0
	v_pk_add_f32 v[110:111], v[86:87], v[86:87] op_sel:[0,1] op_sel_hi:[1,0]
	global_load_dwordx4 v[82:85], v[90:91], off offset:112
	global_load_dwordx4 v[86:89], v[90:91], off offset:96
	global_load_dwordx4 v[100:103], v[90:91], off offset:80
	global_load_dwordx4 v[104:107], v[90:91], off offset:64
	s_waitcnt vmcnt(2)
	v_add_f32_e32 v86, v86, v87
	v_add_f32_e32 v88, v88, v89
	s_waitcnt vmcnt(0)
	v_mov_b32_e32 v109, v104
	v_mov_b32_e32 v111, v105
	v_mov_b32_e32 v113, v106
	v_mov_b32_e32 v115, v107
	v_pk_add_f32 v[90:91], v[108:109], v[110:111]
	v_pk_add_f32 v[104:105], v[112:113], v[114:115]
	v_mov_b32_e32 v87, v84
	v_pk_add_f32 v[90:91], v[90:91], v[104:105]
	v_mov_b32_e32 v104, v101
	v_mov_b32_e32 v105, v102
	v_mov_b32_e32 v101, v103
	v_pk_add_f32 v[100:101], v[104:105], v[100:101]
	v_pk_add_f32 v[90:91], v[90:91], v[90:91] op_sel:[0,1] op_sel_hi:[1,0]
	v_pk_add_f32 v[100:101], v[100:101], v[100:101] op_sel:[0,1] op_sel_hi:[1,0]
	v_mov_b32_e32 v91, v82
	v_mov_b32_e32 v101, v83
	v_mov_b32_e32 v89, v85
	v_pk_add_f32 v[82:83], v[90:91], v[100:101]
	v_pk_add_f32 v[84:85], v[86:87], v[88:89]
	s_nop 0
	v_pk_add_f32 v[82:83], v[82:83], v[84:85]
	s_nop 0
	v_add_f32_e32 v82, v82, v83
	v_fmamk_f32 v82, v82, 0x3a800000, v206
	v_rsq_f32_e32 v82, v82

.LBB0_208:
	s_waitcnt vmcnt(12)
	v_add_f32_e32 v56, v56, v57
	v_add_f32_e32 v57, v58, v59
	v_add_f32_e32 v56, v56, v57
	v_add_f32_e32 v48, v48, v49
	v_add_f32_e32 v49, v50, v51
	v_add_f32_e32 v56, 0, v56
	s_waitcnt vmcnt(11)
	v_add_f32_e32 v57, v60, v61
	v_add_f32_e32 v58, v62, v63
	v_add_f32_e32 v48, v48, v49
	v_add_f32_e32 v36, v36, v37
	v_add_f32_e32 v37, v38, v39
	v_add_f32_e32 v20, v20, v21
	v_add_f32_e32 v21, v22, v23
	v_add_f32_e32 v57, v57, v58
	v_add_f32_e32 v48, v56, v48
	s_waitcnt vmcnt(8)
	v_add_f32_e32 v49, v52, v53
	v_add_f32_e32 v50, v54, v55
	v_add_f32_e32 v36, v36, v37
	v_add_f32_e32 v20, v20, v21
	v_add_f32_e32 v21, v28, v29
	v_add_f32_e32 v22, v30, v31
	v_add_f32_e32 v57, 0, v57
	v_add_f32_e32 v49, v49, v50
	v_add_f32_e32 v36, v48, v36
	v_add_f32_e32 v37, v44, v45
	v_add_f32_e32 v38, v46, v47
	v_add_f32_e32 v21, v21, v22
	s_waitcnt vmcnt(4)
	v_add_f32_e32 v22, v32, v33
	v_add_f32_e32 v23, v34, v35
	v_add_f32_e32 v49, v57, v49
	v_add_f32_e32 v37, v37, v38
	v_add_f32_e32 v20, v36, v20
	v_add_f32_e32 v22, v22, v23
	v_add_f32_e32 v37, v49, v37
	v_add_f32_e32 v20, v20, v22
	s_waitcnt vmcnt(1)
	v_add_f32_e32 v22, v40, v41
	v_add_f32_e32 v23, v42, v43
	v_add_f32_e32 v16, v16, v17
	v_add_f32_e32 v17, v18, v19
	s_cmp_eq_u32 s18, 63
	v_add_f32_e32 v21, v37, v21
	v_add_f32_e32 v22, v22, v23
	v_add_f32_e32 v16, v16, v17
	s_waitcnt vmcnt(0)
	v_add_f32_e32 v17, v24, v25
	v_add_f32_e32 v18, v26, v27
	v_add_f32_e32 v8, v8, v9
	v_add_f32_e32 v9, v10, v11
	s_cselect_b64 s[18:19], -1, 0
	s_lshr_b32 s2, s22, 5
	v_add_f32_e32 v21, v21, v22
	v_add_f32_e32 v16, v20, v16
	v_add_f32_e32 v17, v17, v18
	v_add_f32_e32 v8, v8, v9
	v_add_f32_e32 v9, v12, v13
	v_add_f32_e32 v10, v14, v15
	v_add_f32_e32 v0, v0, v1
	v_add_f32_e32 v1, v2, v3
	s_and_b32 s2, s2, 0x7fffffe
	v_add_f32_e32 v17, v21, v17
	v_add_f32_e32 v8, v16, v8
	v_add_f32_e32 v9, v9, v10
	v_add_f32_e32 v0, v0, v1
	v_add_f32_e32 v1, v4, v5
	v_add_f32_e32 v2, v6, v7
	s_add_i32 s36, s2, s31
	v_add_f32_e32 v9, v17, v9
	v_add_f32_e32 v0, v8, v0
	v_add_f32_e32 v1, v1, v2
	s_and_b64 s[2:3], s[14:15], exec
	v_add_f32_e32 v1, v9, v1
	v_fmamk_f32 v0, v0, 0x3a800000, v206
	s_mov_b32 s2, 0x8408000
	v_rsq_f32_e32 v10, v0
	v_fmamk_f32 v0, v1, 0x3a800000, v206
	s_cselect_b32 s37, s2, 0x186a0000
	s_lshl_b32 s38, s20, 7
	v_rsq_f32_e32 v11, v0
	s_addk_i32 s38, 0x380
	s_mul_hi_i32 s3, s21, 0x2c00
	s_mulk_i32 s21, 0x2c00
	s_add_u32 s2, s34, s21
	v_ashrrev_i32_e32 v91, 31, v90
	s_addc_u32 s3, s35, s3
	s_mov_b32 s39, 0
	v_lshl_add_u64 v[0:1], v[90:91], 1, s[2:3]
	s_branch .LBB0_210

.LBB0_210:
	v_add_co_u32_e32 v2, vcc, 0xfffd7000, v0
	s_bitcmp0_b32 s39, 4
	s_nop 0
	v_addc_co_u32_e32 v3, vcc, -1, v1, vcc
	v_add_co_u32_e32 v4, vcc, 0xfffda000, v0
	s_cselect_b64 s[20:21], -1, 0
	s_nop 0
	v_addc_co_u32_e32 v5, vcc, -1, v1, vcc
	v_add_co_u32_e32 v6, vcc, 0xfffdd000, v0
	s_xor_b64 s[22:23], s[14:15], -1
	s_nop 0
	v_addc_co_u32_e32 v7, vcc, -1, v1, vcc
	v_add_co_u32_e32 v8, vcc, 0xfffdf000, v0
	s_and_b64 s[20:21], s[22:23], s[20:21]
	s_nop 0
	v_addc_co_u32_e32 v9, vcc, -1, v1, vcc
	global_load_dword v45, v[2:3], off offset:-1280 nt
	global_load_dword v44, v[2:3], off offset:-1024 nt
	global_load_dword v43, v[4:5], off offset:-2304 nt
	global_load_dword v42, v[4:5], off offset:-2048 nt
	global_load_dword v41, v[6:7], off offset:-3328 nt
	global_load_dword v40, v[6:7], off offset:-3072 nt
	global_load_dword v39, v[8:9], off offset:-256 nt
	global_load_dword v38, v[8:9], off nt
	v_add_co_u32_e32 v2, vcc, 0xfffe2000, v0
	s_add_i32 s22, s38, s39
	s_nop 0
	v_addc_co_u32_e32 v3, vcc, -1, v1, vcc
	v_add_co_u32_e32 v4, vcc, 0xfffe5000, v0
	s_mov_b64 s[2:3], -1
	s_nop 0
	v_addc_co_u32_e32 v5, vcc, -1, v1, vcc
	v_add_co_u32_e32 v6, vcc, 0xfffe8000, v0
	s_ashr_i32 s22, s22, 5
	s_nop 0
	v_addc_co_u32_e32 v7, vcc, -1, v1, vcc
	v_add_co_u32_e32 v8, vcc, 0xfffea000, v0
	s_nop 1
	v_addc_co_u32_e32 v9, vcc, -1, v1, vcc
	global_load_dword v37, v[2:3], off offset:-1280 nt
	global_load_dword v20, v[2:3], off offset:-1024 nt
	global_load_dword v36, v[4:5], off offset:-2304 nt
	global_load_dword v24, v[4:5], off offset:-2048 nt
	global_load_dword v35, v[6:7], off offset:-3328 nt
	global_load_dword v27, v[6:7], off offset:-3072 nt
	global_load_dword v34, v[8:9], off offset:-256 nt
	global_load_dword v30, v[8:9], off nt
	v_add_co_u32_e32 v2, vcc, 0xfffed000, v0
	s_nop 1
	v_addc_co_u32_e32 v3, vcc, -1, v1, vcc
	v_add_co_u32_e32 v4, vcc, s95, v0
	s_nop 1
	v_addc_co_u32_e32 v5, vcc, -1, v1, vcc
	v_add_co_u32_e32 v6, vcc, 0xffff3000, v0
	s_nop 1
	v_addc_co_u32_e32 v7, vcc, -1, v1, vcc
	v_add_co_u32_e32 v8, vcc, 0xffff5000, v0
	s_nop 1
	v_addc_co_u32_e32 v9, vcc, -1, v1, vcc
	global_load_dword v33, v[2:3], off offset:-1280 nt
	global_load_dword v32, v[2:3], off offset:-1024 nt
	global_load_dword v31, v[4:5], off offset:-2304 nt
	global_load_dword v29, v[4:5], off offset:-2048 nt
	global_load_dword v28, v[6:7], off offset:-3328 nt
	global_load_dword v26, v[6:7], off offset:-3072 nt
	global_load_dword v25, v[8:9], off offset:-256 nt
	global_load_dword v23, v[8:9], off nt
	v_add_co_u32_e32 v2, vcc, 0xffff8000, v0
	s_nop 1
	v_addc_co_u32_e32 v3, vcc, -1, v1, vcc
	v_add_co_u32_e32 v4, vcc, 0xffffb000, v0
	s_nop 1
	v_addc_co_u32_e32 v5, vcc, -1, v1, vcc
	v_add_co_u32_e32 v6, vcc, 0xffffe000, v0
	s_nop 1
	v_addc_co_u32_e32 v7, vcc, -1, v1, vcc
	global_load_dword v22, v[2:3], off offset:-1280 nt
	global_load_dword v21, v[2:3], off offset:-1024 nt
	global_load_dword v19, v[4:5], off offset:-2304 nt
	global_load_dword v18, v[4:5], off offset:-2048 nt
	global_load_dword v17, v[6:7], off offset:-3328 nt
	global_load_dword v16, v[6:7], off offset:-3072 nt
	global_load_dword v13, v[0:1], off offset:-256 nt
	global_load_dword v12, v[0:1], off nt
	s_and_b64 vcc, exec, s[20:21]
	s_cbranch_vccz .LBB0_212
	s_load_dwordx2 s[2:3], s[76:77], 0x18
	s_add_i32 s20, s22, s30
	s_ashr_i32 s21, s20, 31
	s_mul_i32 s24, s20, 0xb000
	s_mul_hi_i32 s23, s20, 0xb000
	s_waitcnt lgkmcnt(0)
	s_add_u32 s2, s2, s24
	s_addc_u32 s3, s3, s23
	v_lshl_add_u64 v[2:3], s[2:3], 0, v[66:67]
	v_lshl_add_u64 v[4:5], s[2:3], 0, v[68:69]
	s_add_u32 s2, s2, 0x5800
	s_addc_u32 s3, s3, 0
	v_lshl_add_u64 v[14:15], s[2:3], 0, v[66:67]
	v_lshl_add_u64 v[46:47], s[2:3], 0, v[68:69]
	global_load_dwordx2 v[8:9], v[2:3], off
	global_load_dwordx2 v[6:7], v[4:5], off
	s_nop 0
	global_load_dwordx2 v[4:5], v[14:15], off
	global_load_dwordx2 v[2:3], v[46:47], off
	s_mov_b64 s[2:3], 0
.LBB0_212:
	s_andn2_b64 vcc, exec, s[2:3]
	s_cbranch_vccnz .LBB0_214
	s_add_i32 s20, s22, s30
	s_ashr_i32 s21, s20, 31
	s_waitcnt vmcnt(2)
	v_mov_b64_e32 v[6:7], v[84:85]
	s_waitcnt vmcnt(0)
	v_mov_b64_e32 v[2:3], v[88:89]
	v_mov_b64_e32 v[8:9], v[82:83]
	v_mov_b64_e32 v[4:5], v[86:87]
.LBB0_214:
	s_cmp_lt_u32 s39, 64
	s_cselect_b64 vcc, -1, 0
	v_and_or_b32 v15, s39, 48, v94
	v_cndmask_b32_e32 v14, v11, v10, vcc
	v_lshlrev_b32_e32 v15, 2, v15
	ds_bpermute_b32 v46, v15, v14
	s_waitcnt vmcnt(31)
	v_lshlrev_b32_e32 v48, 16, v45
	v_and_b32_e32 v49, 0xffff0000, v45
	s_waitcnt vmcnt(30)
	v_lshlrev_b32_e32 v50, 16, v44
	v_and_b32_e32 v51, 0xffff0000, v44
	s_waitcnt lgkmcnt(0)
	v_pk_mul_f32 v[48:49], v[46:47], v[48:49] op_sel_hi:[0,1]
	v_pk_mul_f32 v[44:45], v[46:47], v[50:51] op_sel_hi:[0,1]
	s_waitcnt vmcnt(1)
	v_pk_mul_f32 v[46:47], v[74:75], v[4:5]
	v_lshlrev_b32_e32 v50, 16, v42
	v_pk_fma_f32 v[8:9], v[70:71], v[8:9], v[46:47]
	s_waitcnt vmcnt(0)
	v_pk_mul_f32 v[46:47], v[76:77], v[2:3]
	v_pk_fma_f32 v[8:9], v[78:79], v[48:49], v[8:9]
	v_pk_fma_f32 v[6:7], v[72:73], v[6:7], v[46:47]
	v_mul_f32_e32 v46, 0xbfb8aa3b, v8
	v_exp_f32_e32 v46, v46
	v_pk_fma_f32 v[6:7], v[80:81], v[44:45], v[6:7]
	v_and_b32_e32 v47, 0xffff0000, v43
	v_and_b32_e32 v51, 0xffff0000, v42
	v_add_f32_e32 v46, 1.0, v46
	v_rcp_f32_e32 v46, v46
	s_add_i32 s40, s39, 14
	s_mov_b64 s[22:23], -1
	s_andn2_b64 vcc, exec, s[16:17]
	v_mul_f32_e32 v8, v8, v46
	v_mul_f32_e32 v6, v6, v8
	v_mul_f32_e32 v8, 0xbfb8aa3b, v9
	v_exp_f32_e32 v8, v8
	v_lshlrev_b32_e32 v46, 16, v43
	v_add_f32_e32 v8, 1.0, v8
	v_rcp_f32_e32 v8, v8
	s_nop 0
	v_mul_f32_e32 v8, v9, v8
	v_mul_f32_e32 v7, v7, v8
	ds_bpermute_b32 v8, v15, v14 offset:4
	v_cvt_pk_bf16_f32 v6, v6, v7
	s_waitcnt lgkmcnt(0)
	v_pk_mul_f32 v[46:47], v[8:9], v[46:47] op_sel_hi:[0,1]
	v_pk_mul_f32 v[42:43], v[8:9], v[50:51] op_sel_hi:[0,1]
	v_pk_mul_f32 v[8:9], v[74:75], v[48:49]
	s_nop 0
	v_pk_fma_f32 v[4:5], v[70:71], v[4:5], v[8:9]
	v_pk_mul_f32 v[8:9], v[76:77], v[44:45]
	v_pk_fma_f32 v[4:5], v[78:79], v[46:47], v[4:5]
	v_pk_fma_f32 v[2:3], v[72:73], v[2:3], v[8:9]
	v_mul_f32_e32 v7, 0xbfb8aa3b, v4
	v_exp_f32_e32 v7, v7
	v_pk_fma_f32 v[2:3], v[80:81], v[42:43], v[2:3]
	v_lshlrev_b32_e32 v8, 16, v40
	v_and_b32_e32 v9, 0xffff0000, v40
	v_add_f32_e32 v7, 1.0, v7
	v_rcp_f32_e32 v7, v7
	s_nop 0
	v_mul_f32_e32 v4, v4, v7
	v_mul_f32_e32 v2, v2, v4
	v_mul_f32_e32 v4, 0xbfb8aa3b, v5
	v_exp_f32_e32 v4, v4
	s_nop 0
	v_add_f32_e32 v4, 1.0, v4
	v_rcp_f32_e32 v4, v4
	s_nop 0
	v_mul_f32_e32 v4, v5, v4
	v_mul_f32_e32 v3, v3, v4
	v_cvt_pk_bf16_f32 v7, v2, v3
	ds_bpermute_b32 v2, v15, v14 offset:8
	v_lshlrev_b32_e32 v4, 16, v41
	v_and_b32_e32 v5, 0xffff0000, v41
	v_pk_mul_f32 v[40:41], v[76:77], v[42:43]
	s_waitcnt lgkmcnt(0)
	v_pk_mul_f32 v[4:5], v[2:3], v[4:5] op_sel_hi:[0,1]
	v_pk_mul_f32 v[2:3], v[2:3], v[8:9] op_sel_hi:[0,1]
	v_pk_mul_f32 v[8:9], v[74:75], v[46:47]
	v_pk_fma_f32 v[40:41], v[72:73], v[44:45], v[40:41]
	v_pk_fma_f32 v[8:9], v[70:71], v[48:49], v[8:9]
	v_pk_fma_f32 v[40:41], v[80:81], v[2:3], v[40:41]
	v_pk_fma_f32 v[8:9], v[78:79], v[4:5], v[8:9]
	v_and_b32_e32 v45, 0xffff0000, v39
	v_mul_f32_e32 v44, 0xbfb8aa3b, v8
	v_exp_f32_e32 v44, v44
	v_lshlrev_b32_e32 v48, 16, v38
	v_and_b32_e32 v49, 0xffff0000, v38
	v_add_f32_e32 v44, 1.0, v44
	v_rcp_f32_e32 v44, v44
	s_nop 0
	v_mul_f32_e32 v8, v8, v44
	v_mul_f32_e32 v8, v40, v8
	v_mul_f32_e32 v40, 0xbfb8aa3b, v9
	v_exp_f32_e32 v40, v40
	v_lshlrev_b32_e32 v44, 16, v39
	v_add_f32_e32 v40, 1.0, v40
	v_rcp_f32_e32 v40, v40
	s_nop 0
	v_mul_f32_e32 v9, v9, v40
	ds_bpermute_b32 v40, v15, v14 offset:12
	v_mul_f32_e32 v9, v41, v9
	v_cvt_pk_bf16_f32 v8, v8, v9
	s_waitcnt lgkmcnt(0)
	v_pk_mul_f32 v[44:45], v[40:41], v[44:45] op_sel_hi:[0,1]
	v_pk_mul_f32 v[38:39], v[40:41], v[48:49] op_sel_hi:[0,1]
	v_pk_mul_f32 v[40:41], v[74:75], v[4:5]
	s_nop 0
	v_pk_fma_f32 v[40:41], v[70:71], v[46:47], v[40:41]
	v_pk_mul_f32 v[46:47], v[76:77], v[2:3]
	v_pk_fma_f32 v[40:41], v[78:79], v[44:45], v[40:41]
	v_pk_fma_f32 v[42:43], v[72:73], v[42:43], v[46:47]
	v_mul_f32_e32 v9, 0xbfb8aa3b, v40
	v_exp_f32_e32 v9, v9
	v_pk_fma_f32 v[42:43], v[80:81], v[38:39], v[42:43]
	v_lshlrev_b32_e32 v46, 16, v20
	v_and_b32_e32 v47, 0xffff0000, v20
	v_add_f32_e32 v9, 1.0, v9
	v_rcp_f32_e32 v9, v9
	s_nop 0
	v_mul_f32_e32 v9, v40, v9
	v_mul_f32_e32 v40, 0xbfb8aa3b, v41
	v_exp_f32_e32 v40, v40
	v_mul_f32_e32 v9, v42, v9
	v_lshlrev_b32_e32 v42, 16, v37
	v_add_f32_e32 v40, 1.0, v40
	v_rcp_f32_e32 v40, v40
	s_nop 0
	v_mul_f32_e32 v40, v41, v40
	v_mul_f32_e32 v40, v43, v40
	v_cvt_pk_bf16_f32 v9, v9, v40
	ds_bpermute_b32 v40, v15, v14 offset:16
	v_and_b32_e32 v43, 0xffff0000, v37
	v_and_b32_e32 v37, 0xffff0000, v24
	s_waitcnt lgkmcnt(0)
	v_pk_mul_f32 v[42:43], v[40:41], v[42:43] op_sel_hi:[0,1]
	v_pk_mul_f32 v[40:41], v[40:41], v[46:47] op_sel_hi:[0,1]
	v_pk_mul_f32 v[46:47], v[74:75], v[44:45]
	s_nop 0
	v_pk_fma_f32 v[4:5], v[70:71], v[4:5], v[46:47]
	v_pk_mul_f32 v[46:47], v[76:77], v[38:39]
	v_pk_fma_f32 v[4:5], v[78:79], v[42:43], v[4:5]
	v_pk_fma_f32 v[2:3], v[72:73], v[2:3], v[46:47]
	v_mul_f32_e32 v20, 0xbfb8aa3b, v4
	v_exp_f32_e32 v20, v20
	v_pk_fma_f32 v[2:3], v[80:81], v[40:41], v[2:3]
	v_add_f32_e32 v20, 1.0, v20
	v_rcp_f32_e32 v20, v20
	s_nop 0
	v_mul_f32_e32 v4, v4, v20
	v_mul_f32_e32 v2, v2, v4
	v_mul_f32_e32 v4, 0xbfb8aa3b, v5
	v_exp_f32_e32 v4, v4
	s_nop 0
	v_add_f32_e32 v4, 1.0, v4
	v_rcp_f32_e32 v4, v4
	s_nop 0
	v_mul_f32_e32 v4, v5, v4
	v_mul_f32_e32 v3, v3, v4
	v_cvt_pk_bf16_f32 v20, v2, v3
	ds_bpermute_b32 v2, v15, v14 offset:20
	v_lshlrev_b32_e32 v4, 16, v36
	v_and_b32_e32 v5, 0xffff0000, v36
	v_lshlrev_b32_e32 v36, 16, v24
	s_waitcnt lgkmcnt(0)
	v_pk_mul_f32 v[4:5], v[2:3], v[4:5] op_sel_hi:[0,1]
	v_pk_mul_f32 v[2:3], v[2:3], v[36:37] op_sel_hi:[0,1]
	v_pk_mul_f32 v[36:37], v[74:75], v[42:43]
	s_nop 0
	v_pk_fma_f32 v[36:37], v[70:71], v[44:45], v[36:37]
	v_pk_mul_f32 v[44:45], v[76:77], v[40:41]
	v_pk_fma_f32 v[36:37], v[78:79], v[4:5], v[36:37]
	v_pk_fma_f32 v[38:39], v[72:73], v[38:39], v[44:45]
	v_mul_f32_e32 v24, 0xbfb8aa3b, v36
	v_exp_f32_e32 v24, v24
	v_pk_fma_f32 v[38:39], v[80:81], v[2:3], v[38:39]
	v_lshlrev_b32_e32 v44, 16, v27
	v_and_b32_e32 v45, 0xffff0000, v27
	v_add_f32_e32 v24, 1.0, v24
	v_rcp_f32_e32 v24, v24
	s_nop 0
	v_mul_f32_e32 v24, v36, v24
	v_mul_f32_e32 v36, 0xbfb8aa3b, v37
	v_exp_f32_e32 v36, v36
	v_mul_f32_e32 v24, v38, v24
	v_lshlrev_b32_e32 v38, 16, v35
	v_add_f32_e32 v36, 1.0, v36
	v_rcp_f32_e32 v36, v36
	s_nop 0
	v_mul_f32_e32 v36, v37, v36
	v_mul_f32_e32 v36, v39, v36
	v_cvt_pk_bf16_f32 v24, v24, v36
	ds_bpermute_b32 v36, v15, v14 offset:24
	v_and_b32_e32 v39, 0xffff0000, v35
	s_waitcnt lgkmcnt(0)
	v_pk_mul_f32 v[38:39], v[36:37], v[38:39] op_sel_hi:[0,1]
	v_pk_mul_f32 v[36:37], v[36:37], v[44:45] op_sel_hi:[0,1]
	v_pk_mul_f32 v[44:45], v[74:75], v[4:5]
	s_nop 0
	v_pk_fma_f32 v[42:43], v[70:71], v[42:43], v[44:45]
	v_pk_mul_f32 v[44:45], v[76:77], v[2:3]
	v_pk_fma_f32 v[42:43], v[78:79], v[38:39], v[42:43]
	v_pk_fma_f32 v[40:41], v[72:73], v[40:41], v[44:45]
	v_mul_f32_e32 v27, 0xbfb8aa3b, v42
	v_exp_f32_e32 v27, v27
	v_mul_f32_e32 v35, 0xbfb8aa3b, v43
	v_exp_f32_e32 v35, v35
	v_pk_fma_f32 v[40:41], v[80:81], v[36:37], v[40:41]
	v_add_f32_e32 v27, 1.0, v27
	v_rcp_f32_e32 v27, v27
	v_add_f32_e32 v35, 1.0, v35
	v_rcp_f32_e32 v35, v35
	v_mul_f32_e32 v27, v42, v27
	v_mul_f32_e32 v27, v40, v27
	ds_bpermute_b32 v40, v15, v14 offset:28
	v_mul_f32_e32 v35, v43, v35
	v_mul_f32_e32 v35, v41, v35
	v_lshlrev_b32_e32 v42, 16, v34
	v_and_b32_e32 v43, 0xffff0000, v34
	v_cvt_pk_bf16_f32 v27, v27, v35
	s_waitcnt lgkmcnt(0)
	v_pk_mul_f32 v[34:35], v[40:41], v[42:43] op_sel_hi:[0,1]
	v_lshlrev_b32_e32 v42, 16, v30
	v_and_b32_e32 v43, 0xffff0000, v30
	v_pk_mul_f32 v[40:41], v[40:41], v[42:43] op_sel_hi:[0,1]
	v_pk_mul_f32 v[42:43], v[74:75], v[38:39]
	s_nop 0
	v_pk_fma_f32 v[4:5], v[70:71], v[4:5], v[42:43]
	v_pk_mul_f32 v[42:43], v[76:77], v[36:37]
	v_pk_fma_f32 v[4:5], v[78:79], v[34:35], v[4:5]
	v_pk_fma_f32 v[2:3], v[72:73], v[2:3], v[42:43]
	v_mul_f32_e32 v30, 0xbfb8aa3b, v4
	v_exp_f32_e32 v30, v30
	v_pk_fma_f32 v[2:3], v[80:81], v[40:41], v[2:3]
	v_lshlrev_b32_e32 v42, 16, v32
	v_and_b32_e32 v43, 0xffff0000, v32
	v_add_f32_e32 v30, 1.0, v30
	v_rcp_f32_e32 v30, v30
	s_nop 0
	v_mul_f32_e32 v4, v4, v30
	v_mul_f32_e32 v2, v2, v4
	v_mul_f32_e32 v4, 0xbfb8aa3b, v5
	v_exp_f32_e32 v4, v4
	s_nop 0
	v_add_f32_e32 v4, 1.0, v4
	v_rcp_f32_e32 v4, v4
	s_nop 0
	v_mul_f32_e32 v4, v5, v4
	v_mul_f32_e32 v3, v3, v4
	v_cvt_pk_bf16_f32 v30, v2, v3
	ds_bpermute_b32 v2, v15, v14 offset:32
	v_lshlrev_b32_e32 v4, 16, v33
	v_and_b32_e32 v5, 0xffff0000, v33
	v_pk_mul_f32 v[32:33], v[74:75], v[34:35]
	s_waitcnt lgkmcnt(0)
	v_pk_mul_f32 v[4:5], v[2:3], v[4:5] op_sel_hi:[0,1]
	v_pk_fma_f32 v[32:33], v[70:71], v[38:39], v[32:33]
	v_pk_mul_f32 v[38:39], v[76:77], v[40:41]
	v_pk_fma_f32 v[32:33], v[78:79], v[4:5], v[32:33]
	v_pk_fma_f32 v[36:37], v[72:73], v[36:37], v[38:39]
	v_mul_f32_e32 v38, 0xbfb8aa3b, v32
	v_exp_f32_e32 v38, v38
	v_pk_mul_f32 v[2:3], v[2:3], v[42:43] op_sel_hi:[0,1]
	v_pk_fma_f32 v[36:37], v[80:81], v[2:3], v[36:37]
	v_and_b32_e32 v39, 0xffff0000, v31
	v_add_f32_e32 v38, 1.0, v38
	v_rcp_f32_e32 v38, v38
	v_lshlrev_b32_e32 v42, 16, v29
	v_and_b32_e32 v43, 0xffff0000, v29
	v_mul_f32_e32 v32, v32, v38
	v_mul_f32_e32 v32, v36, v32
	v_mul_f32_e32 v36, 0xbfb8aa3b, v33
	v_exp_f32_e32 v36, v36
	v_lshlrev_b32_e32 v38, 16, v31
	v_add_f32_e32 v36, 1.0, v36
	v_rcp_f32_e32 v36, v36
	s_nop 0
	v_mul_f32_e32 v33, v33, v36
	ds_bpermute_b32 v36, v15, v14 offset:36
	v_mul_f32_e32 v33, v37, v33
	v_cvt_pk_bf16_f32 v32, v32, v33
	s_waitcnt lgkmcnt(0)
	v_pk_mul_f32 v[38:39], v[36:37], v[38:39] op_sel_hi:[0,1]
	v_pk_mul_f32 v[36:37], v[36:37], v[42:43] op_sel_hi:[0,1]
	v_pk_mul_f32 v[42:43], v[74:75], v[4:5]
	s_nop 0
	v_pk_fma_f32 v[34:35], v[70:71], v[34:35], v[42:43]
	v_pk_mul_f32 v[42:43], v[76:77], v[2:3]
	v_pk_fma_f32 v[34:35], v[78:79], v[38:39], v[34:35]
	v_pk_fma_f32 v[40:41], v[72:73], v[40:41], v[42:43]
	v_mul_f32_e32 v29, 0xbfb8aa3b, v34
	v_exp_f32_e32 v29, v29
	v_mul_f32_e32 v31, 0xbfb8aa3b, v35
	v_exp_f32_e32 v31, v31
	v_pk_fma_f32 v[40:41], v[80:81], v[36:37], v[40:41]
	v_add_f32_e32 v29, 1.0, v29
	v_rcp_f32_e32 v29, v29
	v_add_f32_e32 v31, 1.0, v31
	v_rcp_f32_e32 v31, v31
	v_lshlrev_b32_e32 v42, 16, v26
	v_mul_f32_e32 v29, v34, v29
	ds_bpermute_b32 v34, v15, v14 offset:40
	v_mul_f32_e32 v31, v35, v31
	v_mul_f32_e32 v29, v40, v29
	v_mul_f32_e32 v31, v41, v31
	v_lshlrev_b32_e32 v40, 16, v28
	v_and_b32_e32 v41, 0xffff0000, v28
	v_and_b32_e32 v43, 0xffff0000, v26
	s_waitcnt lgkmcnt(0)
	v_pk_mul_f32 v[40:41], v[34:35], v[40:41] op_sel_hi:[0,1]
	v_pk_mul_f32 v[34:35], v[34:35], v[42:43] op_sel_hi:[0,1]
	v_pk_mul_f32 v[42:43], v[74:75], v[38:39]
	v_cvt_pk_bf16_f32 v29, v29, v31
	s_nop 0
	v_pk_fma_f32 v[4:5], v[70:71], v[4:5], v[42:43]
	v_pk_mul_f32 v[42:43], v[76:77], v[36:37]
	v_pk_fma_f32 v[4:5], v[78:79], v[40:41], v[4:5]
	v_pk_fma_f32 v[2:3], v[72:73], v[2:3], v[42:43]
	v_mul_f32_e32 v26, 0xbfb8aa3b, v4
	v_exp_f32_e32 v26, v26
	v_pk_fma_f32 v[2:3], v[80:81], v[34:35], v[2:3]
	v_add_f32_e32 v26, 1.0, v26
	v_rcp_f32_e32 v26, v26
	s_nop 0
	v_mul_f32_e32 v4, v4, v26
	v_mul_f32_e32 v2, v2, v4
	v_mul_f32_e32 v4, 0xbfb8aa3b, v5
	v_exp_f32_e32 v4, v4
	s_nop 0
	v_add_f32_e32 v4, 1.0, v4
	v_rcp_f32_e32 v4, v4
	s_nop 0
	v_mul_f32_e32 v4, v5, v4
	v_mul_f32_e32 v3, v3, v4
	v_cvt_pk_bf16_f32 v26, v2, v3
	ds_bpermute_b32 v2, v15, v14 offset:44
	v_lshlrev_b32_e32 v4, 16, v25
	v_and_b32_e32 v5, 0xffff0000, v25
	s_waitcnt lgkmcnt(0)
	v_pk_mul_f32 v[42:43], v[2:3], v[4:5] op_sel_hi:[0,1]
	v_lshlrev_b32_e32 v4, 16, v23
	v_and_b32_e32 v5, 0xffff0000, v23
	v_pk_mul_f32 v[44:45], v[2:3], v[4:5] op_sel_hi:[0,1]
	v_pk_mul_f32 v[2:3], v[74:75], v[40:41]
	v_pk_mul_f32 v[4:5], v[76:77], v[34:35]
	v_pk_fma_f32 v[2:3], v[70:71], v[38:39], v[2:3]
	v_pk_fma_f32 v[4:5], v[72:73], v[36:37], v[4:5]
	v_pk_fma_f32 v[2:3], v[78:79], v[42:43], v[2:3]
	v_pk_fma_f32 v[4:5], v[80:81], v[44:45], v[4:5]
	v_mul_f32_e32 v23, 0xbfb8aa3b, v2
	v_exp_f32_e32 v23, v23
	s_nop 0
	v_add_f32_e32 v23, 1.0, v23
	v_rcp_f32_e32 v23, v23
	s_nop 0
	v_mul_f32_e32 v2, v2, v23
	v_mul_f32_e32 v2, v4, v2
	v_mul_f32_e32 v4, 0xbfb8aa3b, v3
	v_exp_f32_e32 v4, v4
	s_nop 0
	v_add_f32_e32 v4, 1.0, v4
	v_rcp_f32_e32 v4, v4
	s_nop 0
	v_mul_f32_e32 v3, v3, v4
	v_mul_f32_e32 v3, v5, v3
	v_cvt_pk_bf16_f32 v23, v2, v3
	ds_bpermute_b32 v2, v15, v14 offset:48
	v_lshlrev_b32_e32 v4, 16, v22
	v_and_b32_e32 v5, 0xffff0000, v22
	s_waitcnt lgkmcnt(0)
	v_pk_mul_f32 v[36:37], v[2:3], v[4:5] op_sel_hi:[0,1]
	v_lshlrev_b32_e32 v4, 16, v21
	v_and_b32_e32 v5, 0xffff0000, v21
	v_pk_mul_f32 v[38:39], v[2:3], v[4:5] op_sel_hi:[0,1]
	v_pk_mul_f32 v[2:3], v[74:75], v[42:43]
	v_pk_mul_f32 v[4:5], v[76:77], v[44:45]
	v_pk_fma_f32 v[2:3], v[70:71], v[40:41], v[2:3]
	v_pk_fma_f32 v[4:5], v[72:73], v[34:35], v[4:5]
	v_pk_fma_f32 v[2:3], v[78:79], v[36:37], v[2:3]
	v_pk_fma_f32 v[4:5], v[80:81], v[38:39], v[4:5]
	v_mul_f32_e32 v21, 0xbfb8aa3b, v2
	v_exp_f32_e32 v21, v21
	v_lshlrev_b32_e32 v34, 16, v18
	v_and_b32_e32 v35, 0xffff0000, v18
	v_add_f32_e32 v21, 1.0, v21
	v_rcp_f32_e32 v21, v21
	s_nop 0
	v_mul_f32_e32 v2, v2, v21
	v_mul_f32_e32 v2, v4, v2
	v_mul_f32_e32 v4, 0xbfb8aa3b, v3
	v_exp_f32_e32 v4, v4
	s_nop 0
	v_add_f32_e32 v4, 1.0, v4
	v_rcp_f32_e32 v4, v4
	s_nop 0
	v_mul_f32_e32 v3, v3, v4
	ds_bpermute_b32 v4, v15, v14 offset:52
	v_mul_f32_e32 v3, v5, v3
	v_cvt_pk_bf16_f32 v21, v2, v3
	v_lshlrev_b32_e32 v2, 16, v19
	v_and_b32_e32 v3, 0xffff0000, v19
	v_pk_mul_f32 v[18:19], v[74:75], v[36:37]
	s_waitcnt lgkmcnt(0)
	v_pk_mul_f32 v[2:3], v[4:5], v[2:3] op_sel_hi:[0,1]
	v_pk_fma_f32 v[18:19], v[70:71], v[42:43], v[18:19]
	v_pk_mul_f32 v[4:5], v[4:5], v[34:35] op_sel_hi:[0,1]
	v_pk_fma_f32 v[18:19], v[78:79], v[2:3], v[18:19]
	v_pk_mul_f32 v[34:35], v[76:77], v[38:39]
	v_mul_f32_e32 v22, 0xbfb8aa3b, v18
	v_exp_f32_e32 v22, v22
	v_pk_fma_f32 v[34:35], v[72:73], v[44:45], v[34:35]
	v_add_f32_e32 v22, 1.0, v22
	v_rcp_f32_e32 v22, v22
	v_pk_fma_f32 v[34:35], v[80:81], v[4:5], v[34:35]
	v_mul_f32_e32 v18, v18, v22
	v_mul_f32_e32 v22, 0xbfb8aa3b, v19
	v_exp_f32_e32 v22, v22
	v_mul_f32_e32 v18, v34, v18
	v_lshlrev_b32_e32 v34, 16, v17
	v_add_f32_e32 v22, 1.0, v22
	v_rcp_f32_e32 v22, v22
	s_nop 0
	v_mul_f32_e32 v19, v19, v22
	ds_bpermute_b32 v22, v15, v14 offset:56
	v_mul_f32_e32 v19, v35, v19
	v_and_b32_e32 v35, 0xffff0000, v17
	v_cvt_pk_bf16_f32 v18, v18, v19
	s_waitcnt lgkmcnt(0)
	v_pk_mul_f32 v[82:83], v[22:23], v[34:35] op_sel_hi:[0,1]
	v_lshlrev_b32_e32 v34, 16, v16
	v_and_b32_e32 v35, 0xffff0000, v16
	v_pk_mul_f32 v[16:17], v[74:75], v[2:3]
	v_pk_mul_f32 v[84:85], v[22:23], v[34:35] op_sel_hi:[0,1]
	v_pk_fma_f32 v[16:17], v[70:71], v[36:37], v[16:17]
	v_pk_mul_f32 v[34:35], v[76:77], v[4:5]
	v_pk_fma_f32 v[16:17], v[78:79], v[82:83], v[16:17]
	v_pk_fma_f32 v[34:35], v[72:73], v[38:39], v[34:35]
	v_mul_f32_e32 v19, 0xbfb8aa3b, v16
	v_exp_f32_e32 v19, v19
	v_pk_fma_f32 v[34:35], v[80:81], v[84:85], v[34:35]
	v_add_f32_e32 v19, 1.0, v19
	v_rcp_f32_e32 v19, v19
	s_nop 0
	v_mul_f32_e32 v16, v16, v19
	v_mul_f32_e32 v19, 0xbfb8aa3b, v17
	v_exp_f32_e32 v19, v19
	v_mul_f32_e32 v16, v34, v16
	v_add_f32_e32 v19, 1.0, v19
	v_rcp_f32_e32 v19, v19
	s_nop 0
	v_mul_f32_e32 v17, v17, v19
	v_mul_f32_e32 v17, v35, v17
	v_cvt_pk_bf16_f32 v16, v16, v17
	v_cndmask_b32_e64 v17, 0, 1, s[16:17]
	v_cmp_ne_u32_e64 s[2:3], 1, v17
	s_cbranch_vccz .LBB0_221
	s_andn2_b64 vcc, exec, s[22:23]
	s_cbranch_vccz .LBB0_222
